# mix generic GEMM-unit epilogue (prompt Fourier, pooling): gate and scale loads batched with one counted wait per chunk
# speedup vs baseline: 1.1137x; 1.0048x over previous
.LBB0_1086:
	s_waitcnt vmcnt(0)
	s_mov_b64 s[4:5], -1
	s_and_b64 vcc, exec, s[20:21]
	s_barrier
	s_cbranch_vccz .LBB0_1152
	v_ashrrev_i32_e32 v3, 1, v144
	s_movk_i32 s4, 0xff80
	v_and_or_b32 v3, v3, s4, v161
	v_and_b32_e32 v5, 0xc0, v144
	v_and_b32_e32 v2, 4, v145
	v_add_u32_e32 v5, v5, v2
	v_lshlrev_b32_e32 v2, 2, v5
	v_lshlrev_b32_e32 v5, 1, v5
	v_mad_u32_u24 v0, v3, s92, v5
	v_lshl_add_u32 v1, v3, 11, v5
	v_readlane_b32 s70, v254, 8
	v_readlane_b32 s71, v254, 9
	s_mul_i32 s4, s68, 0xa00
	s_lshl_b32 s5, s14, 1
	s_add_u32 s4, s4, s5
	s_add_u32 s70, s70, s4
	s_addc_u32 s71, s71, 0
	s_lshl_b32 s4, s68, 11
	s_lshl_b32 s5, s12, 1
	s_add_u32 s4, s4, s5
	s_add_u32 s72, s46, s4
	s_addc_u32 s73, s47, 0
	s_cmp_lg_u64 s[0:1], 0
	s_cbranch_scc1 .Lgepi_scale
	s_add_u32 s74, s70, 0x0
	s_addc_u32 s75, s71, 0
	global_load_dwordx2 v[146:147], v0, s[74:75]
	global_load_dwordx2 v[148:149], v0, s[74:75] offset:16
	global_load_dwordx2 v[150:151], v0, s[74:75] offset:32
	global_load_dwordx2 v[152:153], v0, s[74:75] offset:48
	global_load_dwordx2 v[154:155], v0, s[74:75] offset:64
	global_load_dwordx2 v[156:157], v0, s[74:75] offset:80
	global_load_dwordx2 v[158:159], v0, s[74:75] offset:96
	global_load_dwordx2 v[160:161], v0, s[74:75] offset:112
	s_add_u32 s74, s70, 0x14000
	s_addc_u32 s75, s71, 0
	global_load_dwordx2 v[162:163], v0, s[74:75]
	global_load_dwordx2 v[164:165], v0, s[74:75] offset:16
	global_load_dwordx2 v[166:167], v0, s[74:75] offset:32
	global_load_dwordx2 v[168:169], v0, s[74:75] offset:48
	global_load_dwordx2 v[170:171], v0, s[74:75] offset:64
	global_load_dwordx2 v[172:173], v0, s[74:75] offset:80
	global_load_dwordx2 v[174:175], v0, s[74:75] offset:96
	global_load_dwordx2 v[176:177], v0, s[74:75] offset:112
	s_add_u32 s74, s70, 0x28000
	s_addc_u32 s75, s71, 0
	global_load_dwordx2 v[178:179], v0, s[74:75]
	global_load_dwordx2 v[180:181], v0, s[74:75] offset:16
	global_load_dwordx2 v[182:183], v0, s[74:75] offset:32
	global_load_dwordx2 v[184:185], v0, s[74:75] offset:48
	global_load_dwordx2 v[186:187], v0, s[74:75] offset:64
	global_load_dwordx2 v[188:189], v0, s[74:75] offset:80
	global_load_dwordx2 v[190:191], v0, s[74:75] offset:96
	global_load_dwordx2 v[192:193], v0, s[74:75] offset:112
	s_add_u32 s74, s70, 0x3c000
	s_addc_u32 s75, s71, 0
	global_load_dwordx2 v[194:195], v0, s[74:75]
	global_load_dwordx2 v[196:197], v0, s[74:75] offset:16
	global_load_dwordx2 v[198:199], v0, s[74:75] offset:32
	global_load_dwordx2 v[200:201], v0, s[74:75] offset:48
	global_load_dwordx2 v[202:203], v0, s[74:75] offset:64
	global_load_dwordx2 v[204:205], v0, s[74:75] offset:80
	global_load_dwordx2 v[206:207], v0, s[74:75] offset:96
	global_load_dwordx2 v[208:209], v0, s[74:75] offset:112
	s_add_u32 s74, s72, 0x0
	s_addc_u32 s75, s73, 0
	s_waitcnt vmcnt(31)
	v_and_b32_e32 v3, 0xffff0000, v146
	v_lshlrev_b32_e32 v2, 16, v146
	v_pk_mul_f32 v[118:119], v[118:119], v[2:3]
	v_and_b32_e32 v3, 0xffff0000, v147
	v_lshlrev_b32_e32 v2, 16, v147
	v_pk_mul_f32 v[120:121], v[120:121], v[2:3]
	v_cvt_pk_bf16_f32 v146, v118, v119
	v_cvt_pk_bf16_f32 v147, v120, v121
	global_store_dwordx2 v1, v[146:147], s[74:75]
	s_waitcnt vmcnt(31)
	v_and_b32_e32 v3, 0xffff0000, v148
	v_lshlrev_b32_e32 v2, 16, v148
	v_pk_mul_f32 v[122:123], v[122:123], v[2:3]
	v_and_b32_e32 v3, 0xffff0000, v149
	v_lshlrev_b32_e32 v2, 16, v149
	v_pk_mul_f32 v[124:125], v[124:125], v[2:3]
	v_cvt_pk_bf16_f32 v148, v122, v123
	v_cvt_pk_bf16_f32 v149, v124, v125
	global_store_dwordx2 v1, v[148:149], s[74:75] offset:16
	s_waitcnt vmcnt(31)
	v_and_b32_e32 v3, 0xffff0000, v150
	v_lshlrev_b32_e32 v2, 16, v150
	v_pk_mul_f32 v[126:127], v[126:127], v[2:3]
	v_and_b32_e32 v3, 0xffff0000, v151
	v_lshlrev_b32_e32 v2, 16, v151
	v_pk_mul_f32 v[128:129], v[128:129], v[2:3]
	v_cvt_pk_bf16_f32 v150, v126, v127
	v_cvt_pk_bf16_f32 v151, v128, v129
	global_store_dwordx2 v1, v[150:151], s[74:75] offset:32
	s_waitcnt vmcnt(31)
	v_and_b32_e32 v3, 0xffff0000, v152
	v_lshlrev_b32_e32 v2, 16, v152
	v_pk_mul_f32 v[130:131], v[130:131], v[2:3]
	v_and_b32_e32 v3, 0xffff0000, v153
	v_lshlrev_b32_e32 v2, 16, v153
	v_pk_mul_f32 v[132:133], v[132:133], v[2:3]
	v_cvt_pk_bf16_f32 v152, v130, v131
	v_cvt_pk_bf16_f32 v153, v132, v133
	global_store_dwordx2 v1, v[152:153], s[74:75] offset:48
	s_waitcnt vmcnt(31)
	v_and_b32_e32 v3, 0xffff0000, v154
	v_lshlrev_b32_e32 v2, 16, v154
	v_pk_mul_f32 v[102:103], v[102:103], v[2:3]
	v_and_b32_e32 v3, 0xffff0000, v155
	v_lshlrev_b32_e32 v2, 16, v155
	v_pk_mul_f32 v[104:105], v[104:105], v[2:3]
	v_cvt_pk_bf16_f32 v154, v102, v103
	v_cvt_pk_bf16_f32 v155, v104, v105
	global_store_dwordx2 v1, v[154:155], s[74:75] offset:64
	s_waitcnt vmcnt(31)
	v_and_b32_e32 v3, 0xffff0000, v156
	v_lshlrev_b32_e32 v2, 16, v156
	v_pk_mul_f32 v[106:107], v[106:107], v[2:3]
	v_and_b32_e32 v3, 0xffff0000, v157
	v_lshlrev_b32_e32 v2, 16, v157
	v_pk_mul_f32 v[108:109], v[108:109], v[2:3]
	v_cvt_pk_bf16_f32 v156, v106, v107
	v_cvt_pk_bf16_f32 v157, v108, v109
	global_store_dwordx2 v1, v[156:157], s[74:75] offset:80
	s_waitcnt vmcnt(31)
	v_and_b32_e32 v3, 0xffff0000, v158
	v_lshlrev_b32_e32 v2, 16, v158
	v_pk_mul_f32 v[110:111], v[110:111], v[2:3]
	v_and_b32_e32 v3, 0xffff0000, v159
	v_lshlrev_b32_e32 v2, 16, v159
	v_pk_mul_f32 v[112:113], v[112:113], v[2:3]
	v_cvt_pk_bf16_f32 v158, v110, v111
	v_cvt_pk_bf16_f32 v159, v112, v113
	global_store_dwordx2 v1, v[158:159], s[74:75] offset:96
	s_waitcnt vmcnt(31)
	v_and_b32_e32 v3, 0xffff0000, v160
	v_lshlrev_b32_e32 v2, 16, v160
	v_pk_mul_f32 v[114:115], v[114:115], v[2:3]
	v_and_b32_e32 v3, 0xffff0000, v161
	v_lshlrev_b32_e32 v2, 16, v161
	v_pk_mul_f32 v[116:117], v[116:117], v[2:3]
	v_cvt_pk_bf16_f32 v160, v114, v115
	v_cvt_pk_bf16_f32 v161, v116, v117
	global_store_dwordx2 v1, v[160:161], s[74:75] offset:112
	s_add_u32 s74, s72, 0x10000
	s_addc_u32 s75, s73, 0
	s_waitcnt vmcnt(31)
	v_and_b32_e32 v3, 0xffff0000, v162
	v_lshlrev_b32_e32 v2, 16, v162
	v_pk_mul_f32 v[86:87], v[86:87], v[2:3]
	v_and_b32_e32 v3, 0xffff0000, v163
	v_lshlrev_b32_e32 v2, 16, v163
	v_pk_mul_f32 v[88:89], v[88:89], v[2:3]
	v_cvt_pk_bf16_f32 v162, v86, v87
	v_cvt_pk_bf16_f32 v163, v88, v89
	global_store_dwordx2 v1, v[162:163], s[74:75]
	s_waitcnt vmcnt(31)
	v_and_b32_e32 v3, 0xffff0000, v164
	v_lshlrev_b32_e32 v2, 16, v164
	v_pk_mul_f32 v[90:91], v[90:91], v[2:3]
	v_and_b32_e32 v3, 0xffff0000, v165
	v_lshlrev_b32_e32 v2, 16, v165
	v_pk_mul_f32 v[92:93], v[92:93], v[2:3]
	v_cvt_pk_bf16_f32 v164, v90, v91
	v_cvt_pk_bf16_f32 v165, v92, v93
	global_store_dwordx2 v1, v[164:165], s[74:75] offset:16
	s_waitcnt vmcnt(31)
	v_and_b32_e32 v3, 0xffff0000, v166
	v_lshlrev_b32_e32 v2, 16, v166
	v_pk_mul_f32 v[94:95], v[94:95], v[2:3]
	v_and_b32_e32 v3, 0xffff0000, v167
	v_lshlrev_b32_e32 v2, 16, v167
	v_pk_mul_f32 v[96:97], v[96:97], v[2:3]
	v_cvt_pk_bf16_f32 v166, v94, v95
	v_cvt_pk_bf16_f32 v167, v96, v97
	global_store_dwordx2 v1, v[166:167], s[74:75] offset:32
	s_waitcnt vmcnt(31)
	v_and_b32_e32 v3, 0xffff0000, v168
	v_lshlrev_b32_e32 v2, 16, v168
	v_pk_mul_f32 v[98:99], v[98:99], v[2:3]
	v_and_b32_e32 v3, 0xffff0000, v169
	v_lshlrev_b32_e32 v2, 16, v169
	v_pk_mul_f32 v[100:101], v[100:101], v[2:3]
	v_cvt_pk_bf16_f32 v168, v98, v99
	v_cvt_pk_bf16_f32 v169, v100, v101
	global_store_dwordx2 v1, v[168:169], s[74:75] offset:48
	s_waitcnt vmcnt(31)
	v_and_b32_e32 v3, 0xffff0000, v170
	v_lshlrev_b32_e32 v2, 16, v170
	v_pk_mul_f32 v[70:71], v[70:71], v[2:3]
	v_and_b32_e32 v3, 0xffff0000, v171
	v_lshlrev_b32_e32 v2, 16, v171
	v_pk_mul_f32 v[72:73], v[72:73], v[2:3]
	v_cvt_pk_bf16_f32 v170, v70, v71
	v_cvt_pk_bf16_f32 v171, v72, v73
	global_store_dwordx2 v1, v[170:171], s[74:75] offset:64
	s_waitcnt vmcnt(31)
	v_and_b32_e32 v3, 0xffff0000, v172
	v_lshlrev_b32_e32 v2, 16, v172
	v_pk_mul_f32 v[74:75], v[74:75], v[2:3]
	v_and_b32_e32 v3, 0xffff0000, v173
	v_lshlrev_b32_e32 v2, 16, v173
	v_pk_mul_f32 v[76:77], v[76:77], v[2:3]
	v_cvt_pk_bf16_f32 v172, v74, v75
	v_cvt_pk_bf16_f32 v173, v76, v77
	global_store_dwordx2 v1, v[172:173], s[74:75] offset:80
	s_waitcnt vmcnt(31)
	v_and_b32_e32 v3, 0xffff0000, v174
	v_lshlrev_b32_e32 v2, 16, v174
	v_pk_mul_f32 v[78:79], v[78:79], v[2:3]
	v_and_b32_e32 v3, 0xffff0000, v175
	v_lshlrev_b32_e32 v2, 16, v175
	v_pk_mul_f32 v[80:81], v[80:81], v[2:3]
	v_cvt_pk_bf16_f32 v174, v78, v79
	v_cvt_pk_bf16_f32 v175, v80, v81
	global_store_dwordx2 v1, v[174:175], s[74:75] offset:96
	s_waitcnt vmcnt(31)
	v_and_b32_e32 v3, 0xffff0000, v176
	v_lshlrev_b32_e32 v2, 16, v176
	v_pk_mul_f32 v[82:83], v[82:83], v[2:3]
	v_and_b32_e32 v3, 0xffff0000, v177
	v_lshlrev_b32_e32 v2, 16, v177
	v_pk_mul_f32 v[84:85], v[84:85], v[2:3]
	v_cvt_pk_bf16_f32 v176, v82, v83
	v_cvt_pk_bf16_f32 v177, v84, v85
	global_store_dwordx2 v1, v[176:177], s[74:75] offset:112
	s_add_u32 s74, s72, 0x20000
	s_addc_u32 s75, s73, 0
	s_waitcnt vmcnt(31)
	v_and_b32_e32 v3, 0xffff0000, v178
	v_lshlrev_b32_e32 v2, 16, v178
	v_pk_mul_f32 v[54:55], v[54:55], v[2:3]
	v_and_b32_e32 v3, 0xffff0000, v179
	v_lshlrev_b32_e32 v2, 16, v179
	v_pk_mul_f32 v[56:57], v[56:57], v[2:3]
	v_cvt_pk_bf16_f32 v178, v54, v55
	v_cvt_pk_bf16_f32 v179, v56, v57
	global_store_dwordx2 v1, v[178:179], s[74:75]
	s_waitcnt vmcnt(31)
	v_and_b32_e32 v3, 0xffff0000, v180
	v_lshlrev_b32_e32 v2, 16, v180
	v_pk_mul_f32 v[58:59], v[58:59], v[2:3]
	v_and_b32_e32 v3, 0xffff0000, v181
	v_lshlrev_b32_e32 v2, 16, v181
	v_pk_mul_f32 v[60:61], v[60:61], v[2:3]
	v_cvt_pk_bf16_f32 v180, v58, v59
	v_cvt_pk_bf16_f32 v181, v60, v61
	global_store_dwordx2 v1, v[180:181], s[74:75] offset:16
	s_waitcnt vmcnt(31)
	v_and_b32_e32 v3, 0xffff0000, v182
	v_lshlrev_b32_e32 v2, 16, v182
	v_pk_mul_f32 v[62:63], v[62:63], v[2:3]
	v_and_b32_e32 v3, 0xffff0000, v183
	v_lshlrev_b32_e32 v2, 16, v183
	v_pk_mul_f32 v[64:65], v[64:65], v[2:3]
	v_cvt_pk_bf16_f32 v182, v62, v63
	v_cvt_pk_bf16_f32 v183, v64, v65
	global_store_dwordx2 v1, v[182:183], s[74:75] offset:32
	s_waitcnt vmcnt(31)
	v_and_b32_e32 v3, 0xffff0000, v184
	v_lshlrev_b32_e32 v2, 16, v184
	v_pk_mul_f32 v[66:67], v[66:67], v[2:3]
	v_and_b32_e32 v3, 0xffff0000, v185
	v_lshlrev_b32_e32 v2, 16, v185
	v_pk_mul_f32 v[68:69], v[68:69], v[2:3]
	v_cvt_pk_bf16_f32 v184, v66, v67
	v_cvt_pk_bf16_f32 v185, v68, v69
	global_store_dwordx2 v1, v[184:185], s[74:75] offset:48
	s_waitcnt vmcnt(31)
	v_and_b32_e32 v3, 0xffff0000, v186
	v_lshlrev_b32_e32 v2, 16, v186
	v_pk_mul_f32 v[38:39], v[38:39], v[2:3]
	v_and_b32_e32 v3, 0xffff0000, v187
	v_lshlrev_b32_e32 v2, 16, v187
	v_pk_mul_f32 v[40:41], v[40:41], v[2:3]
	v_cvt_pk_bf16_f32 v186, v38, v39
	v_cvt_pk_bf16_f32 v187, v40, v41
	global_store_dwordx2 v1, v[186:187], s[74:75] offset:64
	s_waitcnt vmcnt(31)
	v_and_b32_e32 v3, 0xffff0000, v188
	v_lshlrev_b32_e32 v2, 16, v188
	v_pk_mul_f32 v[42:43], v[42:43], v[2:3]
	v_and_b32_e32 v3, 0xffff0000, v189
	v_lshlrev_b32_e32 v2, 16, v189
	v_pk_mul_f32 v[44:45], v[44:45], v[2:3]
	v_cvt_pk_bf16_f32 v188, v42, v43
	v_cvt_pk_bf16_f32 v189, v44, v45
	global_store_dwordx2 v1, v[188:189], s[74:75] offset:80
	s_waitcnt vmcnt(31)
	v_and_b32_e32 v3, 0xffff0000, v190
	v_lshlrev_b32_e32 v2, 16, v190
	v_pk_mul_f32 v[46:47], v[46:47], v[2:3]
	v_and_b32_e32 v3, 0xffff0000, v191
	v_lshlrev_b32_e32 v2, 16, v191
	v_pk_mul_f32 v[48:49], v[48:49], v[2:3]
	v_cvt_pk_bf16_f32 v190, v46, v47
	v_cvt_pk_bf16_f32 v191, v48, v49
	global_store_dwordx2 v1, v[190:191], s[74:75] offset:96
	s_waitcnt vmcnt(31)
	v_and_b32_e32 v3, 0xffff0000, v192
	v_lshlrev_b32_e32 v2, 16, v192
	v_pk_mul_f32 v[50:51], v[50:51], v[2:3]
	v_and_b32_e32 v3, 0xffff0000, v193
	v_lshlrev_b32_e32 v2, 16, v193
	v_pk_mul_f32 v[52:53], v[52:53], v[2:3]
	v_cvt_pk_bf16_f32 v192, v50, v51
	v_cvt_pk_bf16_f32 v193, v52, v53
	global_store_dwordx2 v1, v[192:193], s[74:75] offset:112
	s_add_u32 s74, s72, 0x30000
	s_addc_u32 s75, s73, 0
	s_waitcnt vmcnt(31)
	v_and_b32_e32 v3, 0xffff0000, v194
	v_lshlrev_b32_e32 v2, 16, v194
	v_pk_mul_f32 v[22:23], v[22:23], v[2:3]
	v_and_b32_e32 v3, 0xffff0000, v195
	v_lshlrev_b32_e32 v2, 16, v195
	v_pk_mul_f32 v[24:25], v[24:25], v[2:3]
	v_cvt_pk_bf16_f32 v194, v22, v23
	v_cvt_pk_bf16_f32 v195, v24, v25
	global_store_dwordx2 v1, v[194:195], s[74:75]
	s_waitcnt vmcnt(31)
	v_and_b32_e32 v3, 0xffff0000, v196
	v_lshlrev_b32_e32 v2, 16, v196
	v_pk_mul_f32 v[26:27], v[26:27], v[2:3]
	v_and_b32_e32 v3, 0xffff0000, v197
	v_lshlrev_b32_e32 v2, 16, v197
	v_pk_mul_f32 v[28:29], v[28:29], v[2:3]
	v_cvt_pk_bf16_f32 v196, v26, v27
	v_cvt_pk_bf16_f32 v197, v28, v29
	global_store_dwordx2 v1, v[196:197], s[74:75] offset:16
	s_waitcnt vmcnt(31)
	v_and_b32_e32 v3, 0xffff0000, v198
	v_lshlrev_b32_e32 v2, 16, v198
	v_pk_mul_f32 v[30:31], v[30:31], v[2:3]
	v_and_b32_e32 v3, 0xffff0000, v199
	v_lshlrev_b32_e32 v2, 16, v199
	v_pk_mul_f32 v[32:33], v[32:33], v[2:3]
	v_cvt_pk_bf16_f32 v198, v30, v31
	v_cvt_pk_bf16_f32 v199, v32, v33
	global_store_dwordx2 v1, v[198:199], s[74:75] offset:32
	s_waitcnt vmcnt(31)
	v_and_b32_e32 v3, 0xffff0000, v200
	v_lshlrev_b32_e32 v2, 16, v200
	v_pk_mul_f32 v[34:35], v[34:35], v[2:3]
	v_and_b32_e32 v3, 0xffff0000, v201
	v_lshlrev_b32_e32 v2, 16, v201
	v_pk_mul_f32 v[36:37], v[36:37], v[2:3]
	v_cvt_pk_bf16_f32 v200, v34, v35
	v_cvt_pk_bf16_f32 v201, v36, v37
	global_store_dwordx2 v1, v[200:201], s[74:75] offset:48
	s_waitcnt vmcnt(31)
	v_and_b32_e32 v3, 0xffff0000, v202
	v_lshlrev_b32_e32 v2, 16, v202
	v_pk_mul_f32 v[6:7], v[6:7], v[2:3]
	v_and_b32_e32 v3, 0xffff0000, v203
	v_lshlrev_b32_e32 v2, 16, v203
	v_pk_mul_f32 v[8:9], v[8:9], v[2:3]
	v_cvt_pk_bf16_f32 v202, v6, v7
	v_cvt_pk_bf16_f32 v203, v8, v9
	global_store_dwordx2 v1, v[202:203], s[74:75] offset:64
	s_waitcnt vmcnt(31)
	v_and_b32_e32 v3, 0xffff0000, v204
	v_lshlrev_b32_e32 v2, 16, v204
	v_pk_mul_f32 v[10:11], v[10:11], v[2:3]
	v_and_b32_e32 v3, 0xffff0000, v205
	v_lshlrev_b32_e32 v2, 16, v205
	v_pk_mul_f32 v[12:13], v[12:13], v[2:3]
	v_cvt_pk_bf16_f32 v204, v10, v11
	v_cvt_pk_bf16_f32 v205, v12, v13
	global_store_dwordx2 v1, v[204:205], s[74:75] offset:80
	s_waitcnt vmcnt(31)
	v_and_b32_e32 v3, 0xffff0000, v206
	v_lshlrev_b32_e32 v2, 16, v206
	v_pk_mul_f32 v[14:15], v[14:15], v[2:3]
	v_and_b32_e32 v3, 0xffff0000, v207
	v_lshlrev_b32_e32 v2, 16, v207
	v_pk_mul_f32 v[16:17], v[16:17], v[2:3]
	v_cvt_pk_bf16_f32 v206, v14, v15
	v_cvt_pk_bf16_f32 v207, v16, v17
	global_store_dwordx2 v1, v[206:207], s[74:75] offset:96
	s_waitcnt vmcnt(31)
	v_and_b32_e32 v3, 0xffff0000, v208
	v_lshlrev_b32_e32 v2, 16, v208
	v_pk_mul_f32 v[18:19], v[18:19], v[2:3]
	v_and_b32_e32 v3, 0xffff0000, v209
	v_lshlrev_b32_e32 v2, 16, v209
	v_pk_mul_f32 v[20:21], v[20:21], v[2:3]
	v_cvt_pk_bf16_f32 v208, v18, v19
	v_cvt_pk_bf16_f32 v209, v20, v21
	global_store_dwordx2 v1, v[208:209], s[74:75] offset:112
	s_branch .Lgepi_done
.Lgepi_scale:
	global_load_dwordx4 v[210:213], v2, s[0:1]
	global_load_dwordx4 v[214:217], v2, s[0:1] offset:32
	global_load_dwordx4 v[218:221], v2, s[0:1] offset:64
	global_load_dwordx4 v[222:225], v2, s[0:1] offset:96
	global_load_dwordx4 v[226:229], v2, s[0:1] offset:128
	global_load_dwordx4 v[230:233], v2, s[0:1] offset:160
	global_load_dwordx4 v[234:237], v2, s[0:1] offset:192
	global_load_dwordx4 v[134:137], v2, s[0:1] offset:224
	s_add_u32 s74, s70, 0x0
	s_addc_u32 s75, s71, 0
	global_load_dwordx2 v[146:147], v0, s[74:75]
	global_load_dwordx2 v[148:149], v0, s[74:75] offset:16
	global_load_dwordx2 v[150:151], v0, s[74:75] offset:32
	global_load_dwordx2 v[152:153], v0, s[74:75] offset:48
	global_load_dwordx2 v[154:155], v0, s[74:75] offset:64
	global_load_dwordx2 v[156:157], v0, s[74:75] offset:80
	global_load_dwordx2 v[158:159], v0, s[74:75] offset:96
	global_load_dwordx2 v[160:161], v0, s[74:75] offset:112
	s_add_u32 s74, s70, 0x14000
	s_addc_u32 s75, s71, 0
	global_load_dwordx2 v[162:163], v0, s[74:75]
	global_load_dwordx2 v[164:165], v0, s[74:75] offset:16
	global_load_dwordx2 v[166:167], v0, s[74:75] offset:32
	global_load_dwordx2 v[168:169], v0, s[74:75] offset:48
	global_load_dwordx2 v[170:171], v0, s[74:75] offset:64
	global_load_dwordx2 v[172:173], v0, s[74:75] offset:80
	global_load_dwordx2 v[174:175], v0, s[74:75] offset:96
	global_load_dwordx2 v[176:177], v0, s[74:75] offset:112
	s_add_u32 s74, s70, 0x28000
	s_addc_u32 s75, s71, 0
	global_load_dwordx2 v[178:179], v0, s[74:75]
	global_load_dwordx2 v[180:181], v0, s[74:75] offset:16
	global_load_dwordx2 v[182:183], v0, s[74:75] offset:32
	global_load_dwordx2 v[184:185], v0, s[74:75] offset:48
	global_load_dwordx2 v[186:187], v0, s[74:75] offset:64
	global_load_dwordx2 v[188:189], v0, s[74:75] offset:80
	global_load_dwordx2 v[190:191], v0, s[74:75] offset:96
	global_load_dwordx2 v[192:193], v0, s[74:75] offset:112
	s_add_u32 s74, s70, 0x3c000
	s_addc_u32 s75, s71, 0
	global_load_dwordx2 v[194:195], v0, s[74:75]
	global_load_dwordx2 v[196:197], v0, s[74:75] offset:16
	global_load_dwordx2 v[198:199], v0, s[74:75] offset:32
	global_load_dwordx2 v[200:201], v0, s[74:75] offset:48
	global_load_dwordx2 v[202:203], v0, s[74:75] offset:64
	global_load_dwordx2 v[204:205], v0, s[74:75] offset:80
	global_load_dwordx2 v[206:207], v0, s[74:75] offset:96
	global_load_dwordx2 v[208:209], v0, s[74:75] offset:112
	s_add_u32 s74, s72, 0x0
	s_addc_u32 s75, s73, 0
	s_waitcnt vmcnt(31)
	v_pk_mul_f32 v[118:119], v[118:119], v[210:211]
	v_pk_mul_f32 v[120:121], v[120:121], v[212:213]
	v_and_b32_e32 v3, 0xffff0000, v146
	v_lshlrev_b32_e32 v2, 16, v146
	v_pk_mul_f32 v[118:119], v[118:119], v[2:3]
	v_and_b32_e32 v3, 0xffff0000, v147
	v_lshlrev_b32_e32 v2, 16, v147
	v_pk_mul_f32 v[120:121], v[120:121], v[2:3]
	v_cvt_pk_bf16_f32 v146, v118, v119
	v_cvt_pk_bf16_f32 v147, v120, v121
	global_store_dwordx2 v1, v[146:147], s[74:75]
	s_waitcnt vmcnt(31)
	v_pk_mul_f32 v[122:123], v[122:123], v[214:215]
	v_pk_mul_f32 v[124:125], v[124:125], v[216:217]
	v_and_b32_e32 v3, 0xffff0000, v148
	v_lshlrev_b32_e32 v2, 16, v148
	v_pk_mul_f32 v[122:123], v[122:123], v[2:3]
	v_and_b32_e32 v3, 0xffff0000, v149
	v_lshlrev_b32_e32 v2, 16, v149
	v_pk_mul_f32 v[124:125], v[124:125], v[2:3]
	v_cvt_pk_bf16_f32 v148, v122, v123
	v_cvt_pk_bf16_f32 v149, v124, v125
	global_store_dwordx2 v1, v[148:149], s[74:75] offset:16
	s_waitcnt vmcnt(31)
	v_pk_mul_f32 v[126:127], v[126:127], v[218:219]
	v_pk_mul_f32 v[128:129], v[128:129], v[220:221]
	v_and_b32_e32 v3, 0xffff0000, v150
	v_lshlrev_b32_e32 v2, 16, v150
	v_pk_mul_f32 v[126:127], v[126:127], v[2:3]
	v_and_b32_e32 v3, 0xffff0000, v151
	v_lshlrev_b32_e32 v2, 16, v151
	v_pk_mul_f32 v[128:129], v[128:129], v[2:3]
	v_cvt_pk_bf16_f32 v150, v126, v127
	v_cvt_pk_bf16_f32 v151, v128, v129
	global_store_dwordx2 v1, v[150:151], s[74:75] offset:32
	s_waitcnt vmcnt(31)
	v_pk_mul_f32 v[130:131], v[130:131], v[222:223]
	v_pk_mul_f32 v[132:133], v[132:133], v[224:225]
	v_and_b32_e32 v3, 0xffff0000, v152
	v_lshlrev_b32_e32 v2, 16, v152
	v_pk_mul_f32 v[130:131], v[130:131], v[2:3]
	v_and_b32_e32 v3, 0xffff0000, v153
	v_lshlrev_b32_e32 v2, 16, v153
	v_pk_mul_f32 v[132:133], v[132:133], v[2:3]
	v_cvt_pk_bf16_f32 v152, v130, v131
	v_cvt_pk_bf16_f32 v153, v132, v133
	global_store_dwordx2 v1, v[152:153], s[74:75] offset:48
	s_waitcnt vmcnt(31)
	v_pk_mul_f32 v[102:103], v[102:103], v[226:227]
	v_pk_mul_f32 v[104:105], v[104:105], v[228:229]
	v_and_b32_e32 v3, 0xffff0000, v154
	v_lshlrev_b32_e32 v2, 16, v154
	v_pk_mul_f32 v[102:103], v[102:103], v[2:3]
	v_and_b32_e32 v3, 0xffff0000, v155
	v_lshlrev_b32_e32 v2, 16, v155
	v_pk_mul_f32 v[104:105], v[104:105], v[2:3]
	v_cvt_pk_bf16_f32 v154, v102, v103
	v_cvt_pk_bf16_f32 v155, v104, v105
	global_store_dwordx2 v1, v[154:155], s[74:75] offset:64
	s_waitcnt vmcnt(31)
	v_pk_mul_f32 v[106:107], v[106:107], v[230:231]
	v_pk_mul_f32 v[108:109], v[108:109], v[232:233]
	v_and_b32_e32 v3, 0xffff0000, v156
	v_lshlrev_b32_e32 v2, 16, v156
	v_pk_mul_f32 v[106:107], v[106:107], v[2:3]
	v_and_b32_e32 v3, 0xffff0000, v157
	v_lshlrev_b32_e32 v2, 16, v157
	v_pk_mul_f32 v[108:109], v[108:109], v[2:3]
	v_cvt_pk_bf16_f32 v156, v106, v107
	v_cvt_pk_bf16_f32 v157, v108, v109
	global_store_dwordx2 v1, v[156:157], s[74:75] offset:80
	s_waitcnt vmcnt(31)
	v_pk_mul_f32 v[110:111], v[110:111], v[234:235]
	v_pk_mul_f32 v[112:113], v[112:113], v[236:237]
	v_and_b32_e32 v3, 0xffff0000, v158
	v_lshlrev_b32_e32 v2, 16, v158
	v_pk_mul_f32 v[110:111], v[110:111], v[2:3]
	v_and_b32_e32 v3, 0xffff0000, v159
	v_lshlrev_b32_e32 v2, 16, v159
	v_pk_mul_f32 v[112:113], v[112:113], v[2:3]
	v_cvt_pk_bf16_f32 v158, v110, v111
	v_cvt_pk_bf16_f32 v159, v112, v113
	global_store_dwordx2 v1, v[158:159], s[74:75] offset:96
	s_waitcnt vmcnt(31)
	v_pk_mul_f32 v[114:115], v[114:115], v[134:135]
	v_pk_mul_f32 v[116:117], v[116:117], v[136:137]
	v_and_b32_e32 v3, 0xffff0000, v160
	v_lshlrev_b32_e32 v2, 16, v160
	v_pk_mul_f32 v[114:115], v[114:115], v[2:3]
	v_and_b32_e32 v3, 0xffff0000, v161
	v_lshlrev_b32_e32 v2, 16, v161
	v_pk_mul_f32 v[116:117], v[116:117], v[2:3]
	v_cvt_pk_bf16_f32 v160, v114, v115
	v_cvt_pk_bf16_f32 v161, v116, v117
	global_store_dwordx2 v1, v[160:161], s[74:75] offset:112
	s_add_u32 s74, s72, 0x10000
	s_addc_u32 s75, s73, 0
	s_waitcnt vmcnt(31)
	v_pk_mul_f32 v[86:87], v[86:87], v[210:211]
	v_pk_mul_f32 v[88:89], v[88:89], v[212:213]
	v_and_b32_e32 v3, 0xffff0000, v162
	v_lshlrev_b32_e32 v2, 16, v162
	v_pk_mul_f32 v[86:87], v[86:87], v[2:3]
	v_and_b32_e32 v3, 0xffff0000, v163
	v_lshlrev_b32_e32 v2, 16, v163
	v_pk_mul_f32 v[88:89], v[88:89], v[2:3]
	v_cvt_pk_bf16_f32 v162, v86, v87
	v_cvt_pk_bf16_f32 v163, v88, v89
	global_store_dwordx2 v1, v[162:163], s[74:75]
	s_waitcnt vmcnt(31)
	v_pk_mul_f32 v[90:91], v[90:91], v[214:215]
	v_pk_mul_f32 v[92:93], v[92:93], v[216:217]
	v_and_b32_e32 v3, 0xffff0000, v164
	v_lshlrev_b32_e32 v2, 16, v164
	v_pk_mul_f32 v[90:91], v[90:91], v[2:3]
	v_and_b32_e32 v3, 0xffff0000, v165
	v_lshlrev_b32_e32 v2, 16, v165
	v_pk_mul_f32 v[92:93], v[92:93], v[2:3]
	v_cvt_pk_bf16_f32 v164, v90, v91
	v_cvt_pk_bf16_f32 v165, v92, v93
	global_store_dwordx2 v1, v[164:165], s[74:75] offset:16
	s_waitcnt vmcnt(31)
	v_pk_mul_f32 v[94:95], v[94:95], v[218:219]
	v_pk_mul_f32 v[96:97], v[96:97], v[220:221]
	v_and_b32_e32 v3, 0xffff0000, v166
	v_lshlrev_b32_e32 v2, 16, v166
	v_pk_mul_f32 v[94:95], v[94:95], v[2:3]
	v_and_b32_e32 v3, 0xffff0000, v167
	v_lshlrev_b32_e32 v2, 16, v167
	v_pk_mul_f32 v[96:97], v[96:97], v[2:3]
	v_cvt_pk_bf16_f32 v166, v94, v95
	v_cvt_pk_bf16_f32 v167, v96, v97
	global_store_dwordx2 v1, v[166:167], s[74:75] offset:32
	s_waitcnt vmcnt(31)
	v_pk_mul_f32 v[98:99], v[98:99], v[222:223]
	v_pk_mul_f32 v[100:101], v[100:101], v[224:225]
	v_and_b32_e32 v3, 0xffff0000, v168
	v_lshlrev_b32_e32 v2, 16, v168
	v_pk_mul_f32 v[98:99], v[98:99], v[2:3]
	v_and_b32_e32 v3, 0xffff0000, v169
	v_lshlrev_b32_e32 v2, 16, v169
	v_pk_mul_f32 v[100:101], v[100:101], v[2:3]
	v_cvt_pk_bf16_f32 v168, v98, v99
	v_cvt_pk_bf16_f32 v169, v100, v101
	global_store_dwordx2 v1, v[168:169], s[74:75] offset:48
	s_waitcnt vmcnt(31)
	v_pk_mul_f32 v[70:71], v[70:71], v[226:227]
	v_pk_mul_f32 v[72:73], v[72:73], v[228:229]
	v_and_b32_e32 v3, 0xffff0000, v170
	v_lshlrev_b32_e32 v2, 16, v170
	v_pk_mul_f32 v[70:71], v[70:71], v[2:3]
	v_and_b32_e32 v3, 0xffff0000, v171
	v_lshlrev_b32_e32 v2, 16, v171
	v_pk_mul_f32 v[72:73], v[72:73], v[2:3]
	v_cvt_pk_bf16_f32 v170, v70, v71
	v_cvt_pk_bf16_f32 v171, v72, v73
	global_store_dwordx2 v1, v[170:171], s[74:75] offset:64
	s_waitcnt vmcnt(31)
	v_pk_mul_f32 v[74:75], v[74:75], v[230:231]
	v_pk_mul_f32 v[76:77], v[76:77], v[232:233]
	v_and_b32_e32 v3, 0xffff0000, v172
	v_lshlrev_b32_e32 v2, 16, v172
	v_pk_mul_f32 v[74:75], v[74:75], v[2:3]
	v_and_b32_e32 v3, 0xffff0000, v173
	v_lshlrev_b32_e32 v2, 16, v173
	v_pk_mul_f32 v[76:77], v[76:77], v[2:3]
	v_cvt_pk_bf16_f32 v172, v74, v75
	v_cvt_pk_bf16_f32 v173, v76, v77
	global_store_dwordx2 v1, v[172:173], s[74:75] offset:80
	s_waitcnt vmcnt(31)
	v_pk_mul_f32 v[78:79], v[78:79], v[234:235]
	v_pk_mul_f32 v[80:81], v[80:81], v[236:237]
	v_and_b32_e32 v3, 0xffff0000, v174
	v_lshlrev_b32_e32 v2, 16, v174
	v_pk_mul_f32 v[78:79], v[78:79], v[2:3]
	v_and_b32_e32 v3, 0xffff0000, v175
	v_lshlrev_b32_e32 v2, 16, v175
	v_pk_mul_f32 v[80:81], v[80:81], v[2:3]
	v_cvt_pk_bf16_f32 v174, v78, v79
	v_cvt_pk_bf16_f32 v175, v80, v81
	global_store_dwordx2 v1, v[174:175], s[74:75] offset:96
	s_waitcnt vmcnt(31)
	v_pk_mul_f32 v[82:83], v[82:83], v[134:135]
	v_pk_mul_f32 v[84:85], v[84:85], v[136:137]
	v_and_b32_e32 v3, 0xffff0000, v176
	v_lshlrev_b32_e32 v2, 16, v176
	v_pk_mul_f32 v[82:83], v[82:83], v[2:3]
	v_and_b32_e32 v3, 0xffff0000, v177
	v_lshlrev_b32_e32 v2, 16, v177
	v_pk_mul_f32 v[84:85], v[84:85], v[2:3]
	v_cvt_pk_bf16_f32 v176, v82, v83
	v_cvt_pk_bf16_f32 v177, v84, v85
	global_store_dwordx2 v1, v[176:177], s[74:75] offset:112
	s_add_u32 s74, s72, 0x20000
	s_addc_u32 s75, s73, 0
	s_waitcnt vmcnt(31)
	v_pk_mul_f32 v[54:55], v[54:55], v[210:211]
	v_pk_mul_f32 v[56:57], v[56:57], v[212:213]
	v_and_b32_e32 v3, 0xffff0000, v178
	v_lshlrev_b32_e32 v2, 16, v178
	v_pk_mul_f32 v[54:55], v[54:55], v[2:3]
	v_and_b32_e32 v3, 0xffff0000, v179
	v_lshlrev_b32_e32 v2, 16, v179
	v_pk_mul_f32 v[56:57], v[56:57], v[2:3]
	v_cvt_pk_bf16_f32 v178, v54, v55
	v_cvt_pk_bf16_f32 v179, v56, v57
	global_store_dwordx2 v1, v[178:179], s[74:75]
	s_waitcnt vmcnt(31)
	v_pk_mul_f32 v[58:59], v[58:59], v[214:215]
	v_pk_mul_f32 v[60:61], v[60:61], v[216:217]
	v_and_b32_e32 v3, 0xffff0000, v180
	v_lshlrev_b32_e32 v2, 16, v180
	v_pk_mul_f32 v[58:59], v[58:59], v[2:3]
	v_and_b32_e32 v3, 0xffff0000, v181
	v_lshlrev_b32_e32 v2, 16, v181
	v_pk_mul_f32 v[60:61], v[60:61], v[2:3]
	v_cvt_pk_bf16_f32 v180, v58, v59
	v_cvt_pk_bf16_f32 v181, v60, v61
	global_store_dwordx2 v1, v[180:181], s[74:75] offset:16
	s_waitcnt vmcnt(31)
	v_pk_mul_f32 v[62:63], v[62:63], v[218:219]
	v_pk_mul_f32 v[64:65], v[64:65], v[220:221]
	v_and_b32_e32 v3, 0xffff0000, v182
	v_lshlrev_b32_e32 v2, 16, v182
	v_pk_mul_f32 v[62:63], v[62:63], v[2:3]
	v_and_b32_e32 v3, 0xffff0000, v183
	v_lshlrev_b32_e32 v2, 16, v183
	v_pk_mul_f32 v[64:65], v[64:65], v[2:3]
	v_cvt_pk_bf16_f32 v182, v62, v63
	v_cvt_pk_bf16_f32 v183, v64, v65
	global_store_dwordx2 v1, v[182:183], s[74:75] offset:32
	s_waitcnt vmcnt(31)
	v_pk_mul_f32 v[66:67], v[66:67], v[222:223]
	v_pk_mul_f32 v[68:69], v[68:69], v[224:225]
	v_and_b32_e32 v3, 0xffff0000, v184
	v_lshlrev_b32_e32 v2, 16, v184
	v_pk_mul_f32 v[66:67], v[66:67], v[2:3]
	v_and_b32_e32 v3, 0xffff0000, v185
	v_lshlrev_b32_e32 v2, 16, v185
	v_pk_mul_f32 v[68:69], v[68:69], v[2:3]
	v_cvt_pk_bf16_f32 v184, v66, v67
	v_cvt_pk_bf16_f32 v185, v68, v69
	global_store_dwordx2 v1, v[184:185], s[74:75] offset:48
	s_waitcnt vmcnt(31)
	v_pk_mul_f32 v[38:39], v[38:39], v[226:227]
	v_pk_mul_f32 v[40:41], v[40:41], v[228:229]
	v_and_b32_e32 v3, 0xffff0000, v186
	v_lshlrev_b32_e32 v2, 16, v186
	v_pk_mul_f32 v[38:39], v[38:39], v[2:3]
	v_and_b32_e32 v3, 0xffff0000, v187
	v_lshlrev_b32_e32 v2, 16, v187
	v_pk_mul_f32 v[40:41], v[40:41], v[2:3]
	v_cvt_pk_bf16_f32 v186, v38, v39
	v_cvt_pk_bf16_f32 v187, v40, v41
	global_store_dwordx2 v1, v[186:187], s[74:75] offset:64
	s_waitcnt vmcnt(31)
	v_pk_mul_f32 v[42:43], v[42:43], v[230:231]
	v_pk_mul_f32 v[44:45], v[44:45], v[232:233]
	v_and_b32_e32 v3, 0xffff0000, v188
	v_lshlrev_b32_e32 v2, 16, v188
	v_pk_mul_f32 v[42:43], v[42:43], v[2:3]
	v_and_b32_e32 v3, 0xffff0000, v189
	v_lshlrev_b32_e32 v2, 16, v189
	v_pk_mul_f32 v[44:45], v[44:45], v[2:3]
	v_cvt_pk_bf16_f32 v188, v42, v43
	v_cvt_pk_bf16_f32 v189, v44, v45
	global_store_dwordx2 v1, v[188:189], s[74:75] offset:80
	s_waitcnt vmcnt(31)
	v_pk_mul_f32 v[46:47], v[46:47], v[234:235]
	v_pk_mul_f32 v[48:49], v[48:49], v[236:237]
	v_and_b32_e32 v3, 0xffff0000, v190
	v_lshlrev_b32_e32 v2, 16, v190
	v_pk_mul_f32 v[46:47], v[46:47], v[2:3]
	v_and_b32_e32 v3, 0xffff0000, v191
	v_lshlrev_b32_e32 v2, 16, v191
	v_pk_mul_f32 v[48:49], v[48:49], v[2:3]
	v_cvt_pk_bf16_f32 v190, v46, v47
	v_cvt_pk_bf16_f32 v191, v48, v49
	global_store_dwordx2 v1, v[190:191], s[74:75] offset:96
	s_waitcnt vmcnt(31)
	v_pk_mul_f32 v[50:51], v[50:51], v[134:135]
	v_pk_mul_f32 v[52:53], v[52:53], v[136:137]
	v_and_b32_e32 v3, 0xffff0000, v192
	v_lshlrev_b32_e32 v2, 16, v192
	v_pk_mul_f32 v[50:51], v[50:51], v[2:3]
	v_and_b32_e32 v3, 0xffff0000, v193
	v_lshlrev_b32_e32 v2, 16, v193
	v_pk_mul_f32 v[52:53], v[52:53], v[2:3]
	v_cvt_pk_bf16_f32 v192, v50, v51
	v_cvt_pk_bf16_f32 v193, v52, v53
	global_store_dwordx2 v1, v[192:193], s[74:75] offset:112
	s_add_u32 s74, s72, 0x30000
	s_addc_u32 s75, s73, 0
	s_waitcnt vmcnt(31)
	v_pk_mul_f32 v[22:23], v[22:23], v[210:211]
	v_pk_mul_f32 v[24:25], v[24:25], v[212:213]
	v_and_b32_e32 v3, 0xffff0000, v194
	v_lshlrev_b32_e32 v2, 16, v194
	v_pk_mul_f32 v[22:23], v[22:23], v[2:3]
	v_and_b32_e32 v3, 0xffff0000, v195
	v_lshlrev_b32_e32 v2, 16, v195
	v_pk_mul_f32 v[24:25], v[24:25], v[2:3]
	v_cvt_pk_bf16_f32 v194, v22, v23
	v_cvt_pk_bf16_f32 v195, v24, v25
	global_store_dwordx2 v1, v[194:195], s[74:75]
	s_waitcnt vmcnt(31)
	v_pk_mul_f32 v[26:27], v[26:27], v[214:215]
	v_pk_mul_f32 v[28:29], v[28:29], v[216:217]
	v_and_b32_e32 v3, 0xffff0000, v196
	v_lshlrev_b32_e32 v2, 16, v196
	v_pk_mul_f32 v[26:27], v[26:27], v[2:3]
	v_and_b32_e32 v3, 0xffff0000, v197
	v_lshlrev_b32_e32 v2, 16, v197
	v_pk_mul_f32 v[28:29], v[28:29], v[2:3]
	v_cvt_pk_bf16_f32 v196, v26, v27
	v_cvt_pk_bf16_f32 v197, v28, v29
	global_store_dwordx2 v1, v[196:197], s[74:75] offset:16
	s_waitcnt vmcnt(31)
	v_pk_mul_f32 v[30:31], v[30:31], v[218:219]
	v_pk_mul_f32 v[32:33], v[32:33], v[220:221]
	v_and_b32_e32 v3, 0xffff0000, v198
	v_lshlrev_b32_e32 v2, 16, v198
	v_pk_mul_f32 v[30:31], v[30:31], v[2:3]
	v_and_b32_e32 v3, 0xffff0000, v199
	v_lshlrev_b32_e32 v2, 16, v199
	v_pk_mul_f32 v[32:33], v[32:33], v[2:3]
	v_cvt_pk_bf16_f32 v198, v30, v31
	v_cvt_pk_bf16_f32 v199, v32, v33
	global_store_dwordx2 v1, v[198:199], s[74:75] offset:32
	s_waitcnt vmcnt(31)
	v_pk_mul_f32 v[34:35], v[34:35], v[222:223]
	v_pk_mul_f32 v[36:37], v[36:37], v[224:225]
	v_and_b32_e32 v3, 0xffff0000, v200
	v_lshlrev_b32_e32 v2, 16, v200
	v_pk_mul_f32 v[34:35], v[34:35], v[2:3]
	v_and_b32_e32 v3, 0xffff0000, v201
	v_lshlrev_b32_e32 v2, 16, v201
	v_pk_mul_f32 v[36:37], v[36:37], v[2:3]
	v_cvt_pk_bf16_f32 v200, v34, v35
	v_cvt_pk_bf16_f32 v201, v36, v37
	global_store_dwordx2 v1, v[200:201], s[74:75] offset:48
	s_waitcnt vmcnt(31)
	v_pk_mul_f32 v[6:7], v[6:7], v[226:227]
	v_pk_mul_f32 v[8:9], v[8:9], v[228:229]
	v_and_b32_e32 v3, 0xffff0000, v202
	v_lshlrev_b32_e32 v2, 16, v202
	v_pk_mul_f32 v[6:7], v[6:7], v[2:3]
	v_and_b32_e32 v3, 0xffff0000, v203
	v_lshlrev_b32_e32 v2, 16, v203
	v_pk_mul_f32 v[8:9], v[8:9], v[2:3]
	v_cvt_pk_bf16_f32 v202, v6, v7
	v_cvt_pk_bf16_f32 v203, v8, v9
	global_store_dwordx2 v1, v[202:203], s[74:75] offset:64
	s_waitcnt vmcnt(31)
	v_pk_mul_f32 v[10:11], v[10:11], v[230:231]
	v_pk_mul_f32 v[12:13], v[12:13], v[232:233]
	v_and_b32_e32 v3, 0xffff0000, v204
	v_lshlrev_b32_e32 v2, 16, v204
	v_pk_mul_f32 v[10:11], v[10:11], v[2:3]
	v_and_b32_e32 v3, 0xffff0000, v205
	v_lshlrev_b32_e32 v2, 16, v205
	v_pk_mul_f32 v[12:13], v[12:13], v[2:3]
	v_cvt_pk_bf16_f32 v204, v10, v11
	v_cvt_pk_bf16_f32 v205, v12, v13
	global_store_dwordx2 v1, v[204:205], s[74:75] offset:80
	s_waitcnt vmcnt(31)
	v_pk_mul_f32 v[14:15], v[14:15], v[234:235]
	v_pk_mul_f32 v[16:17], v[16:17], v[236:237]
	v_and_b32_e32 v3, 0xffff0000, v206
	v_lshlrev_b32_e32 v2, 16, v206
	v_pk_mul_f32 v[14:15], v[14:15], v[2:3]
	v_and_b32_e32 v3, 0xffff0000, v207
	v_lshlrev_b32_e32 v2, 16, v207
	v_pk_mul_f32 v[16:17], v[16:17], v[2:3]
	v_cvt_pk_bf16_f32 v206, v14, v15
	v_cvt_pk_bf16_f32 v207, v16, v17
	global_store_dwordx2 v1, v[206:207], s[74:75] offset:96
	s_waitcnt vmcnt(31)
	v_pk_mul_f32 v[18:19], v[18:19], v[134:135]
	v_pk_mul_f32 v[20:21], v[20:21], v[136:137]
	v_and_b32_e32 v3, 0xffff0000, v208
	v_lshlrev_b32_e32 v2, 16, v208
	v_pk_mul_f32 v[18:19], v[18:19], v[2:3]
	v_and_b32_e32 v3, 0xffff0000, v209
	v_lshlrev_b32_e32 v2, 16, v209
	v_pk_mul_f32 v[20:21], v[20:21], v[2:3]
	v_cvt_pk_bf16_f32 v208, v18, v19
	v_cvt_pk_bf16_f32 v209, v20, v21
	global_store_dwordx2 v1, v[208:209], s[74:75] offset:112
.Lgepi_done:
	s_mov_b64 s[4:5], 0
.LBB0_1152:
	s_and_b64 vcc, exec, s[4:5]
	s_cbranch_vccz .LBB0_1154
	v_readlane_b32 s70, v254, 8
	v_readlane_b32 s71, v254, 9
	v_ashrrev_i32_e32 v0, 1, v144
	s_movk_i32 s0, 0xff80
	v_and_or_b32 v0, v0, s0, v161
	v_lshlrev_b32_e32 v2, 6, v145
	v_and_or_b32 v2, v2, s33, v160
	v_add_u32_e32 v2, s68, v2
	v_lshlrev_b32_e32 v0, 1, v0
	v_mad_u32_u24 v1, v2, s92, v0
	v_lshl_add_u32 v3, v2, 11, v0
	s_mov_b64 s[72:73], s[46:47]
	v_mov_b32_e32 v146, 0
	v_mov_b32_e32 v147, 0
	v_mov_b32_e32 v148, 0
	v_mov_b32_e32 v149, 0
	v_mov_b32_e32 v150, 0
	v_mov_b32_e32 v151, 0
	v_mov_b32_e32 v152, 0
	v_mov_b32_e32 v153, 0
	v_mov_b32_e32 v154, 0
	v_mov_b32_e32 v155, 0
	v_mov_b32_e32 v156, 0
	v_mov_b32_e32 v157, 0
	v_mov_b32_e32 v158, 0
	v_mov_b32_e32 v159, 0
	v_mov_b32_e32 v160, 0
	v_mov_b32_e32 v161, 0
	v_mov_b32_e32 v162, 0
	v_mov_b32_e32 v163, 0
	v_mov_b32_e32 v164, 0
	v_mov_b32_e32 v165, 0
	v_mov_b32_e32 v166, 0
	v_mov_b32_e32 v167, 0
	v_mov_b32_e32 v168, 0
	v_mov_b32_e32 v169, 0
	v_mov_b32_e32 v170, 0
	v_mov_b32_e32 v171, 0
	v_mov_b32_e32 v172, 0
	v_mov_b32_e32 v173, 0
	v_mov_b32_e32 v174, 0
	v_mov_b32_e32 v175, 0
	v_mov_b32_e32 v176, 0
	v_mov_b32_e32 v177, 0
	global_load_short_d16_hi v146, v1, s[70:71]
	global_load_short_d16_hi v147, v1, s[70:71] offset:64
	global_load_short_d16_hi v148, v1, s[70:71] offset:128
	global_load_short_d16_hi v149, v1, s[70:71] offset:192
	s_add_u32 s70, s70, 0x28000
	s_addc_u32 s71, s71, 0
	global_load_short_d16_hi v150, v1, s[70:71]
	global_load_short_d16_hi v151, v1, s[70:71] offset:64
	global_load_short_d16_hi v152, v1, s[70:71] offset:128
	global_load_short_d16_hi v153, v1, s[70:71] offset:192
	s_add_u32 s70, s70, 0x28000
	s_addc_u32 s71, s71, 0
	global_load_short_d16_hi v154, v1, s[70:71]
	global_load_short_d16_hi v155, v1, s[70:71] offset:64
	global_load_short_d16_hi v156, v1, s[70:71] offset:128
	global_load_short_d16_hi v157, v1, s[70:71] offset:192
	s_add_u32 s70, s70, 0x28000
	s_addc_u32 s71, s71, 0
	global_load_short_d16_hi v158, v1, s[70:71]
	global_load_short_d16_hi v159, v1, s[70:71] offset:64
	global_load_short_d16_hi v160, v1, s[70:71] offset:128
	global_load_short_d16_hi v161, v1, s[70:71] offset:192
	s_add_u32 s70, s70, 0xc8000
	s_addc_u32 s71, s71, 0
	global_load_short_d16_hi v162, v1, s[70:71]
	global_load_short_d16_hi v163, v1, s[70:71] offset:64
	global_load_short_d16_hi v164, v1, s[70:71] offset:128
	global_load_short_d16_hi v165, v1, s[70:71] offset:192
	s_add_u32 s70, s70, 0x28000
	s_addc_u32 s71, s71, 0
	global_load_short_d16_hi v166, v1, s[70:71]
	global_load_short_d16_hi v167, v1, s[70:71] offset:64
	global_load_short_d16_hi v168, v1, s[70:71] offset:128
	global_load_short_d16_hi v169, v1, s[70:71] offset:192
	s_add_u32 s70, s70, 0x28000
	s_addc_u32 s71, s71, 0
	global_load_short_d16_hi v170, v1, s[70:71]
	global_load_short_d16_hi v171, v1, s[70:71] offset:64
	global_load_short_d16_hi v172, v1, s[70:71] offset:128
	global_load_short_d16_hi v173, v1, s[70:71] offset:192
	s_add_u32 s70, s70, 0x28000
	s_addc_u32 s71, s71, 0
	global_load_short_d16_hi v174, v1, s[70:71]
	global_load_short_d16_hi v175, v1, s[70:71] offset:64
	global_load_short_d16_hi v176, v1, s[70:71] offset:128
	global_load_short_d16_hi v177, v1, s[70:71] offset:192
	s_add_u32 s70, s70, 0xc8000
	s_addc_u32 s71, s71, 0
	s_waitcnt vmcnt(16)
	v_mul_f32_e32 v178, v118, v146
	v_cvt_pk_bf16_f32 v178, v178, v178
	global_store_short v3, v178, s[72:73]
	v_mul_f32_e32 v179, v86, v147
	v_cvt_pk_bf16_f32 v179, v179, v179
	global_store_short v3, v179, s[72:73] offset:64
	v_mul_f32_e32 v180, v54, v148
	v_cvt_pk_bf16_f32 v180, v180, v180
	global_store_short v3, v180, s[72:73] offset:128
	v_mul_f32_e32 v181, v22, v149
	v_cvt_pk_bf16_f32 v181, v181, v181
	global_store_short v3, v181, s[72:73] offset:192
	s_add_u32 s72, s72, 0x20000
	s_addc_u32 s73, s73, 0
	v_mul_f32_e32 v178, v119, v150
	v_cvt_pk_bf16_f32 v178, v178, v178
	global_store_short v3, v178, s[72:73]
	v_mul_f32_e32 v179, v87, v151
	v_cvt_pk_bf16_f32 v179, v179, v179
	global_store_short v3, v179, s[72:73] offset:64
	v_mul_f32_e32 v180, v55, v152
	v_cvt_pk_bf16_f32 v180, v180, v180
	global_store_short v3, v180, s[72:73] offset:128
	v_mul_f32_e32 v181, v23, v153
	v_cvt_pk_bf16_f32 v181, v181, v181
	global_store_short v3, v181, s[72:73] offset:192
	s_add_u32 s72, s72, 0x20000
	s_addc_u32 s73, s73, 0
	v_mul_f32_e32 v178, v120, v154
	v_cvt_pk_bf16_f32 v178, v178, v178
	global_store_short v3, v178, s[72:73]
	v_mul_f32_e32 v179, v88, v155
	v_cvt_pk_bf16_f32 v179, v179, v179
	global_store_short v3, v179, s[72:73] offset:64
	v_mul_f32_e32 v180, v56, v156
	v_cvt_pk_bf16_f32 v180, v180, v180
	global_store_short v3, v180, s[72:73] offset:128
	v_mul_f32_e32 v181, v24, v157
	v_cvt_pk_bf16_f32 v181, v181, v181
	global_store_short v3, v181, s[72:73] offset:192
	s_add_u32 s72, s72, 0x20000
	s_addc_u32 s73, s73, 0
	v_mul_f32_e32 v178, v121, v158
	v_cvt_pk_bf16_f32 v178, v178, v178
	global_store_short v3, v178, s[72:73]
	v_mul_f32_e32 v179, v89, v159
	v_cvt_pk_bf16_f32 v179, v179, v179
	global_store_short v3, v179, s[72:73] offset:64
	v_mul_f32_e32 v180, v57, v160
	v_cvt_pk_bf16_f32 v180, v180, v180
	global_store_short v3, v180, s[72:73] offset:128
	v_mul_f32_e32 v181, v25, v161
	v_cvt_pk_bf16_f32 v181, v181, v181
	global_store_short v3, v181, s[72:73] offset:192
	s_add_u32 s72, s72, 0xa0000
	s_addc_u32 s73, s73, 0
	global_load_short_d16_hi v146, v1, s[70:71]
	global_load_short_d16_hi v147, v1, s[70:71] offset:64
	global_load_short_d16_hi v148, v1, s[70:71] offset:128
	global_load_short_d16_hi v149, v1, s[70:71] offset:192
	s_add_u32 s70, s70, 0x28000
	s_addc_u32 s71, s71, 0
	global_load_short_d16_hi v150, v1, s[70:71]
	global_load_short_d16_hi v151, v1, s[70:71] offset:64
	global_load_short_d16_hi v152, v1, s[70:71] offset:128
	global_load_short_d16_hi v153, v1, s[70:71] offset:192
	s_add_u32 s70, s70, 0x28000
	s_addc_u32 s71, s71, 0
	global_load_short_d16_hi v154, v1, s[70:71]
	global_load_short_d16_hi v155, v1, s[70:71] offset:64
	global_load_short_d16_hi v156, v1, s[70:71] offset:128
	global_load_short_d16_hi v157, v1, s[70:71] offset:192
	s_add_u32 s70, s70, 0x28000
	s_addc_u32 s71, s71, 0
	global_load_short_d16_hi v158, v1, s[70:71]
	global_load_short_d16_hi v159, v1, s[70:71] offset:64
	global_load_short_d16_hi v160, v1, s[70:71] offset:128
	global_load_short_d16_hi v161, v1, s[70:71] offset:192
	s_add_u32 s70, s70, 0xc8000
	s_addc_u32 s71, s71, 0
	s_waitcnt vmcnt(32)
	v_mul_f32_e32 v178, v122, v162
	v_cvt_pk_bf16_f32 v178, v178, v178
	global_store_short v3, v178, s[72:73]
	v_mul_f32_e32 v179, v90, v163
	v_cvt_pk_bf16_f32 v179, v179, v179
	global_store_short v3, v179, s[72:73] offset:64
	v_mul_f32_e32 v180, v58, v164
	v_cvt_pk_bf16_f32 v180, v180, v180
	global_store_short v3, v180, s[72:73] offset:128
	v_mul_f32_e32 v181, v26, v165
	v_cvt_pk_bf16_f32 v181, v181, v181
	global_store_short v3, v181, s[72:73] offset:192
	s_add_u32 s72, s72, 0x20000
	s_addc_u32 s73, s73, 0
	v_mul_f32_e32 v178, v123, v166
	v_cvt_pk_bf16_f32 v178, v178, v178
	global_store_short v3, v178, s[72:73]
	v_mul_f32_e32 v179, v91, v167
	v_cvt_pk_bf16_f32 v179, v179, v179
	global_store_short v3, v179, s[72:73] offset:64
	v_mul_f32_e32 v180, v59, v168
	v_cvt_pk_bf16_f32 v180, v180, v180
	global_store_short v3, v180, s[72:73] offset:128
	v_mul_f32_e32 v181, v27, v169
	v_cvt_pk_bf16_f32 v181, v181, v181
	global_store_short v3, v181, s[72:73] offset:192
	s_add_u32 s72, s72, 0x20000
	s_addc_u32 s73, s73, 0
	v_mul_f32_e32 v178, v124, v170
	v_cvt_pk_bf16_f32 v178, v178, v178
	global_store_short v3, v178, s[72:73]
	v_mul_f32_e32 v179, v92, v171
	v_cvt_pk_bf16_f32 v179, v179, v179
	global_store_short v3, v179, s[72:73] offset:64
	v_mul_f32_e32 v180, v60, v172
	v_cvt_pk_bf16_f32 v180, v180, v180
	global_store_short v3, v180, s[72:73] offset:128
	v_mul_f32_e32 v181, v28, v173
	v_cvt_pk_bf16_f32 v181, v181, v181
	global_store_short v3, v181, s[72:73] offset:192
	s_add_u32 s72, s72, 0x20000
	s_addc_u32 s73, s73, 0
	v_mul_f32_e32 v178, v125, v174
	v_cvt_pk_bf16_f32 v178, v178, v178
	global_store_short v3, v178, s[72:73]
	v_mul_f32_e32 v179, v93, v175
	v_cvt_pk_bf16_f32 v179, v179, v179
	global_store_short v3, v179, s[72:73] offset:64
	v_mul_f32_e32 v180, v61, v176
	v_cvt_pk_bf16_f32 v180, v180, v180
	global_store_short v3, v180, s[72:73] offset:128
	v_mul_f32_e32 v181, v29, v177
	v_cvt_pk_bf16_f32 v181, v181, v181
	global_store_short v3, v181, s[72:73] offset:192
	s_add_u32 s72, s72, 0xa0000
	s_addc_u32 s73, s73, 0
	global_load_short_d16_hi v162, v1, s[70:71]
	global_load_short_d16_hi v163, v1, s[70:71] offset:64
	global_load_short_d16_hi v164, v1, s[70:71] offset:128
	global_load_short_d16_hi v165, v1, s[70:71] offset:192
	s_add_u32 s70, s70, 0x28000
	s_addc_u32 s71, s71, 0
	global_load_short_d16_hi v166, v1, s[70:71]
	global_load_short_d16_hi v167, v1, s[70:71] offset:64
	global_load_short_d16_hi v168, v1, s[70:71] offset:128
	global_load_short_d16_hi v169, v1, s[70:71] offset:192
	s_add_u32 s70, s70, 0x28000
	s_addc_u32 s71, s71, 0
	global_load_short_d16_hi v170, v1, s[70:71]
	global_load_short_d16_hi v171, v1, s[70:71] offset:64
	global_load_short_d16_hi v172, v1, s[70:71] offset:128
	global_load_short_d16_hi v173, v1, s[70:71] offset:192
	s_add_u32 s70, s70, 0x28000
	s_addc_u32 s71, s71, 0
	global_load_short_d16_hi v174, v1, s[70:71]
	global_load_short_d16_hi v175, v1, s[70:71] offset:64
	global_load_short_d16_hi v176, v1, s[70:71] offset:128
	global_load_short_d16_hi v177, v1, s[70:71] offset:192
	s_add_u32 s70, s70, 0xc8000
	s_addc_u32 s71, s71, 0
	s_waitcnt vmcnt(32)
	v_mul_f32_e32 v178, v126, v146
	v_cvt_pk_bf16_f32 v178, v178, v178
	global_store_short v3, v178, s[72:73]
	v_mul_f32_e32 v179, v94, v147
	v_cvt_pk_bf16_f32 v179, v179, v179
	global_store_short v3, v179, s[72:73] offset:64
	v_mul_f32_e32 v180, v62, v148
	v_cvt_pk_bf16_f32 v180, v180, v180
	global_store_short v3, v180, s[72:73] offset:128
	v_mul_f32_e32 v181, v30, v149
	v_cvt_pk_bf16_f32 v181, v181, v181
	global_store_short v3, v181, s[72:73] offset:192
	s_add_u32 s72, s72, 0x20000
	s_addc_u32 s73, s73, 0
	v_mul_f32_e32 v178, v127, v150
	v_cvt_pk_bf16_f32 v178, v178, v178
	global_store_short v3, v178, s[72:73]
	v_mul_f32_e32 v179, v95, v151
	v_cvt_pk_bf16_f32 v179, v179, v179
	global_store_short v3, v179, s[72:73] offset:64
	v_mul_f32_e32 v180, v63, v152
	v_cvt_pk_bf16_f32 v180, v180, v180
	global_store_short v3, v180, s[72:73] offset:128
	v_mul_f32_e32 v181, v31, v153
	v_cvt_pk_bf16_f32 v181, v181, v181
	global_store_short v3, v181, s[72:73] offset:192
	s_add_u32 s72, s72, 0x20000
	s_addc_u32 s73, s73, 0
	v_mul_f32_e32 v178, v128, v154
	v_cvt_pk_bf16_f32 v178, v178, v178
	global_store_short v3, v178, s[72:73]
	v_mul_f32_e32 v179, v96, v155
	v_cvt_pk_bf16_f32 v179, v179, v179
	global_store_short v3, v179, s[72:73] offset:64
	v_mul_f32_e32 v180, v64, v156
	v_cvt_pk_bf16_f32 v180, v180, v180
	global_store_short v3, v180, s[72:73] offset:128
	v_mul_f32_e32 v181, v32, v157
	v_cvt_pk_bf16_f32 v181, v181, v181
	global_store_short v3, v181, s[72:73] offset:192
	s_add_u32 s72, s72, 0x20000
	s_addc_u32 s73, s73, 0
	v_mul_f32_e32 v178, v129, v158
	v_cvt_pk_bf16_f32 v178, v178, v178
	global_store_short v3, v178, s[72:73]
	v_mul_f32_e32 v179, v97, v159
	v_cvt_pk_bf16_f32 v179, v179, v179
	global_store_short v3, v179, s[72:73] offset:64
	v_mul_f32_e32 v180, v65, v160
	v_cvt_pk_bf16_f32 v180, v180, v180
	global_store_short v3, v180, s[72:73] offset:128
	v_mul_f32_e32 v181, v33, v161
	v_cvt_pk_bf16_f32 v181, v181, v181
	global_store_short v3, v181, s[72:73] offset:192
	s_add_u32 s72, s72, 0xa0000
	s_addc_u32 s73, s73, 0
	global_load_short_d16_hi v146, v1, s[70:71]
	global_load_short_d16_hi v147, v1, s[70:71] offset:64
	global_load_short_d16_hi v148, v1, s[70:71] offset:128
	global_load_short_d16_hi v149, v1, s[70:71] offset:192
	s_add_u32 s70, s70, 0x28000
	s_addc_u32 s71, s71, 0
	global_load_short_d16_hi v150, v1, s[70:71]
	global_load_short_d16_hi v151, v1, s[70:71] offset:64
	global_load_short_d16_hi v152, v1, s[70:71] offset:128
	global_load_short_d16_hi v153, v1, s[70:71] offset:192
	s_add_u32 s70, s70, 0x28000
	s_addc_u32 s71, s71, 0
	global_load_short_d16_hi v154, v1, s[70:71]
	global_load_short_d16_hi v155, v1, s[70:71] offset:64
	global_load_short_d16_hi v156, v1, s[70:71] offset:128
	global_load_short_d16_hi v157, v1, s[70:71] offset:192
	s_add_u32 s70, s70, 0x28000
	s_addc_u32 s71, s71, 0
	global_load_short_d16_hi v158, v1, s[70:71]
	global_load_short_d16_hi v159, v1, s[70:71] offset:64
	global_load_short_d16_hi v160, v1, s[70:71] offset:128
	global_load_short_d16_hi v161, v1, s[70:71] offset:192
	s_add_u32 s70, s70, 0xc8000
	s_addc_u32 s71, s71, 0
	s_waitcnt vmcnt(32)
	v_mul_f32_e32 v178, v130, v162
	v_cvt_pk_bf16_f32 v178, v178, v178
	global_store_short v3, v178, s[72:73]
	v_mul_f32_e32 v179, v98, v163
	v_cvt_pk_bf16_f32 v179, v179, v179
	global_store_short v3, v179, s[72:73] offset:64
	v_mul_f32_e32 v180, v66, v164
	v_cvt_pk_bf16_f32 v180, v180, v180
	global_store_short v3, v180, s[72:73] offset:128
	v_mul_f32_e32 v181, v34, v165
	v_cvt_pk_bf16_f32 v181, v181, v181
	global_store_short v3, v181, s[72:73] offset:192
	s_add_u32 s72, s72, 0x20000
	s_addc_u32 s73, s73, 0
	v_mul_f32_e32 v178, v131, v166
	v_cvt_pk_bf16_f32 v178, v178, v178
	global_store_short v3, v178, s[72:73]
	v_mul_f32_e32 v179, v99, v167
	v_cvt_pk_bf16_f32 v179, v179, v179
	global_store_short v3, v179, s[72:73] offset:64
	v_mul_f32_e32 v180, v67, v168
	v_cvt_pk_bf16_f32 v180, v180, v180
	global_store_short v3, v180, s[72:73] offset:128
	v_mul_f32_e32 v181, v35, v169
	v_cvt_pk_bf16_f32 v181, v181, v181
	global_store_short v3, v181, s[72:73] offset:192
	s_add_u32 s72, s72, 0x20000
	s_addc_u32 s73, s73, 0
	v_mul_f32_e32 v178, v132, v170
	v_cvt_pk_bf16_f32 v178, v178, v178
	global_store_short v3, v178, s[72:73]
	v_mul_f32_e32 v179, v100, v171
	v_cvt_pk_bf16_f32 v179, v179, v179
	global_store_short v3, v179, s[72:73] offset:64
	v_mul_f32_e32 v180, v68, v172
	v_cvt_pk_bf16_f32 v180, v180, v180
	global_store_short v3, v180, s[72:73] offset:128
	v_mul_f32_e32 v181, v36, v173
	v_cvt_pk_bf16_f32 v181, v181, v181
	global_store_short v3, v181, s[72:73] offset:192
	s_add_u32 s72, s72, 0x20000
	s_addc_u32 s73, s73, 0
	v_mul_f32_e32 v178, v133, v174
	v_cvt_pk_bf16_f32 v178, v178, v178
	global_store_short v3, v178, s[72:73]
	v_mul_f32_e32 v179, v101, v175
	v_cvt_pk_bf16_f32 v179, v179, v179
	global_store_short v3, v179, s[72:73] offset:64
	v_mul_f32_e32 v180, v69, v176
	v_cvt_pk_bf16_f32 v180, v180, v180
	global_store_short v3, v180, s[72:73] offset:128
	v_mul_f32_e32 v181, v37, v177
	v_cvt_pk_bf16_f32 v181, v181, v181
	global_store_short v3, v181, s[72:73] offset:192
	s_add_u32 s72, s72, 0xa0000
	s_addc_u32 s73, s73, 0
	global_load_short_d16_hi v162, v1, s[70:71]
	global_load_short_d16_hi v163, v1, s[70:71] offset:64
	global_load_short_d16_hi v164, v1, s[70:71] offset:128
	global_load_short_d16_hi v165, v1, s[70:71] offset:192
	s_add_u32 s70, s70, 0x28000
	s_addc_u32 s71, s71, 0
	global_load_short_d16_hi v166, v1, s[70:71]
	global_load_short_d16_hi v167, v1, s[70:71] offset:64
	global_load_short_d16_hi v168, v1, s[70:71] offset:128
	global_load_short_d16_hi v169, v1, s[70:71] offset:192
	s_add_u32 s70, s70, 0x28000
	s_addc_u32 s71, s71, 0
	global_load_short_d16_hi v170, v1, s[70:71]
	global_load_short_d16_hi v171, v1, s[70:71] offset:64
	global_load_short_d16_hi v172, v1, s[70:71] offset:128
	global_load_short_d16_hi v173, v1, s[70:71] offset:192
	s_add_u32 s70, s70, 0x28000
	s_addc_u32 s71, s71, 0
	global_load_short_d16_hi v174, v1, s[70:71]
	global_load_short_d16_hi v175, v1, s[70:71] offset:64
	global_load_short_d16_hi v176, v1, s[70:71] offset:128
	global_load_short_d16_hi v177, v1, s[70:71] offset:192
	s_add_u32 s70, s70, 0xc8000
	s_addc_u32 s71, s71, 0
	s_waitcnt vmcnt(32)
	v_mul_f32_e32 v178, v102, v146
	v_cvt_pk_bf16_f32 v178, v178, v178
	global_store_short v3, v178, s[72:73]
	v_mul_f32_e32 v179, v70, v147
	v_cvt_pk_bf16_f32 v179, v179, v179
	global_store_short v3, v179, s[72:73] offset:64
	v_mul_f32_e32 v180, v38, v148
	v_cvt_pk_bf16_f32 v180, v180, v180
	global_store_short v3, v180, s[72:73] offset:128
	v_mul_f32_e32 v181, v6, v149
	v_cvt_pk_bf16_f32 v181, v181, v181
	global_store_short v3, v181, s[72:73] offset:192
	s_add_u32 s72, s72, 0x20000
	s_addc_u32 s73, s73, 0
	v_mul_f32_e32 v178, v103, v150
	v_cvt_pk_bf16_f32 v178, v178, v178
	global_store_short v3, v178, s[72:73]
	v_mul_f32_e32 v179, v71, v151
	v_cvt_pk_bf16_f32 v179, v179, v179
	global_store_short v3, v179, s[72:73] offset:64
	v_mul_f32_e32 v180, v39, v152
	v_cvt_pk_bf16_f32 v180, v180, v180
	global_store_short v3, v180, s[72:73] offset:128
	v_mul_f32_e32 v181, v7, v153
	v_cvt_pk_bf16_f32 v181, v181, v181
	global_store_short v3, v181, s[72:73] offset:192
	s_add_u32 s72, s72, 0x20000
	s_addc_u32 s73, s73, 0
	v_mul_f32_e32 v178, v104, v154
	v_cvt_pk_bf16_f32 v178, v178, v178
	global_store_short v3, v178, s[72:73]
	v_mul_f32_e32 v179, v72, v155
	v_cvt_pk_bf16_f32 v179, v179, v179
	global_store_short v3, v179, s[72:73] offset:64
	v_mul_f32_e32 v180, v40, v156
	v_cvt_pk_bf16_f32 v180, v180, v180
	global_store_short v3, v180, s[72:73] offset:128
	v_mul_f32_e32 v181, v8, v157
	v_cvt_pk_bf16_f32 v181, v181, v181
	global_store_short v3, v181, s[72:73] offset:192
	s_add_u32 s72, s72, 0x20000
	s_addc_u32 s73, s73, 0
	v_mul_f32_e32 v178, v105, v158
	v_cvt_pk_bf16_f32 v178, v178, v178
	global_store_short v3, v178, s[72:73]
	v_mul_f32_e32 v179, v73, v159
	v_cvt_pk_bf16_f32 v179, v179, v179
	global_store_short v3, v179, s[72:73] offset:64
	v_mul_f32_e32 v180, v41, v160
	v_cvt_pk_bf16_f32 v180, v180, v180
	global_store_short v3, v180, s[72:73] offset:128
	v_mul_f32_e32 v181, v9, v161
	v_cvt_pk_bf16_f32 v181, v181, v181
	global_store_short v3, v181, s[72:73] offset:192
	s_add_u32 s72, s72, 0xa0000
	s_addc_u32 s73, s73, 0
	global_load_short_d16_hi v146, v1, s[70:71]
	global_load_short_d16_hi v147, v1, s[70:71] offset:64
	global_load_short_d16_hi v148, v1, s[70:71] offset:128
	global_load_short_d16_hi v149, v1, s[70:71] offset:192
	s_add_u32 s70, s70, 0x28000
	s_addc_u32 s71, s71, 0
	global_load_short_d16_hi v150, v1, s[70:71]
	global_load_short_d16_hi v151, v1, s[70:71] offset:64
	global_load_short_d16_hi v152, v1, s[70:71] offset:128
	global_load_short_d16_hi v153, v1, s[70:71] offset:192
	s_add_u32 s70, s70, 0x28000
	s_addc_u32 s71, s71, 0
	global_load_short_d16_hi v154, v1, s[70:71]
	global_load_short_d16_hi v155, v1, s[70:71] offset:64
	global_load_short_d16_hi v156, v1, s[70:71] offset:128
	global_load_short_d16_hi v157, v1, s[70:71] offset:192
	s_add_u32 s70, s70, 0x28000
	s_addc_u32 s71, s71, 0
	global_load_short_d16_hi v158, v1, s[70:71]
	global_load_short_d16_hi v159, v1, s[70:71] offset:64
	global_load_short_d16_hi v160, v1, s[70:71] offset:128
	global_load_short_d16_hi v161, v1, s[70:71] offset:192
	s_add_u32 s70, s70, 0xc8000
	s_addc_u32 s71, s71, 0
	s_waitcnt vmcnt(32)
	v_mul_f32_e32 v178, v106, v162
	v_cvt_pk_bf16_f32 v178, v178, v178
	global_store_short v3, v178, s[72:73]
	v_mul_f32_e32 v179, v74, v163
	v_cvt_pk_bf16_f32 v179, v179, v179
	global_store_short v3, v179, s[72:73] offset:64
	v_mul_f32_e32 v180, v42, v164
	v_cvt_pk_bf16_f32 v180, v180, v180
	global_store_short v3, v180, s[72:73] offset:128
	v_mul_f32_e32 v181, v10, v165
	v_cvt_pk_bf16_f32 v181, v181, v181
	global_store_short v3, v181, s[72:73] offset:192
	s_add_u32 s72, s72, 0x20000
	s_addc_u32 s73, s73, 0
	v_mul_f32_e32 v178, v107, v166
	v_cvt_pk_bf16_f32 v178, v178, v178
	global_store_short v3, v178, s[72:73]
	v_mul_f32_e32 v179, v75, v167
	v_cvt_pk_bf16_f32 v179, v179, v179
	global_store_short v3, v179, s[72:73] offset:64
	v_mul_f32_e32 v180, v43, v168
	v_cvt_pk_bf16_f32 v180, v180, v180
	global_store_short v3, v180, s[72:73] offset:128
	v_mul_f32_e32 v181, v11, v169
	v_cvt_pk_bf16_f32 v181, v181, v181
	global_store_short v3, v181, s[72:73] offset:192
	s_add_u32 s72, s72, 0x20000
	s_addc_u32 s73, s73, 0
	v_mul_f32_e32 v178, v108, v170
	v_cvt_pk_bf16_f32 v178, v178, v178
	global_store_short v3, v178, s[72:73]
	v_mul_f32_e32 v179, v76, v171
	v_cvt_pk_bf16_f32 v179, v179, v179
	global_store_short v3, v179, s[72:73] offset:64
	v_mul_f32_e32 v180, v44, v172
	v_cvt_pk_bf16_f32 v180, v180, v180
	global_store_short v3, v180, s[72:73] offset:128
	v_mul_f32_e32 v181, v12, v173
	v_cvt_pk_bf16_f32 v181, v181, v181
	global_store_short v3, v181, s[72:73] offset:192
	s_add_u32 s72, s72, 0x20000
	s_addc_u32 s73, s73, 0
	v_mul_f32_e32 v178, v109, v174
	v_cvt_pk_bf16_f32 v178, v178, v178
	global_store_short v3, v178, s[72:73]
	v_mul_f32_e32 v179, v77, v175
	v_cvt_pk_bf16_f32 v179, v179, v179
	global_store_short v3, v179, s[72:73] offset:64
	v_mul_f32_e32 v180, v45, v176
	v_cvt_pk_bf16_f32 v180, v180, v180
	global_store_short v3, v180, s[72:73] offset:128
	v_mul_f32_e32 v181, v13, v177
	v_cvt_pk_bf16_f32 v181, v181, v181
	global_store_short v3, v181, s[72:73] offset:192
	s_add_u32 s72, s72, 0xa0000
	s_addc_u32 s73, s73, 0
	global_load_short_d16_hi v162, v1, s[70:71]
	global_load_short_d16_hi v163, v1, s[70:71] offset:64
	global_load_short_d16_hi v164, v1, s[70:71] offset:128
	global_load_short_d16_hi v165, v1, s[70:71] offset:192
	s_add_u32 s70, s70, 0x28000
	s_addc_u32 s71, s71, 0
	global_load_short_d16_hi v166, v1, s[70:71]
	global_load_short_d16_hi v167, v1, s[70:71] offset:64
	global_load_short_d16_hi v168, v1, s[70:71] offset:128
	global_load_short_d16_hi v169, v1, s[70:71] offset:192
	s_add_u32 s70, s70, 0x28000
	s_addc_u32 s71, s71, 0
	global_load_short_d16_hi v170, v1, s[70:71]
	global_load_short_d16_hi v171, v1, s[70:71] offset:64
	global_load_short_d16_hi v172, v1, s[70:71] offset:128
	global_load_short_d16_hi v173, v1, s[70:71] offset:192
	s_add_u32 s70, s70, 0x28000
	s_addc_u32 s71, s71, 0
	global_load_short_d16_hi v174, v1, s[70:71]
	global_load_short_d16_hi v175, v1, s[70:71] offset:64
	global_load_short_d16_hi v176, v1, s[70:71] offset:128
	global_load_short_d16_hi v177, v1, s[70:71] offset:192
	s_waitcnt vmcnt(32)
	v_mul_f32_e32 v178, v110, v146
	v_cvt_pk_bf16_f32 v178, v178, v178
	global_store_short v3, v178, s[72:73]
	v_mul_f32_e32 v179, v78, v147
	v_cvt_pk_bf16_f32 v179, v179, v179
	global_store_short v3, v179, s[72:73] offset:64
	v_mul_f32_e32 v180, v46, v148
	v_cvt_pk_bf16_f32 v180, v180, v180
	global_store_short v3, v180, s[72:73] offset:128
	v_mul_f32_e32 v181, v14, v149
	v_cvt_pk_bf16_f32 v181, v181, v181
	global_store_short v3, v181, s[72:73] offset:192
	s_add_u32 s72, s72, 0x20000
	s_addc_u32 s73, s73, 0
	v_mul_f32_e32 v178, v111, v150
	v_cvt_pk_bf16_f32 v178, v178, v178
	global_store_short v3, v178, s[72:73]
	v_mul_f32_e32 v179, v79, v151
	v_cvt_pk_bf16_f32 v179, v179, v179
	global_store_short v3, v179, s[72:73] offset:64
	v_mul_f32_e32 v180, v47, v152
	v_cvt_pk_bf16_f32 v180, v180, v180
	global_store_short v3, v180, s[72:73] offset:128
	v_mul_f32_e32 v181, v15, v153
	v_cvt_pk_bf16_f32 v181, v181, v181
	global_store_short v3, v181, s[72:73] offset:192
	s_add_u32 s72, s72, 0x20000
	s_addc_u32 s73, s73, 0
	v_mul_f32_e32 v178, v112, v154
	v_cvt_pk_bf16_f32 v178, v178, v178
	global_store_short v3, v178, s[72:73]
	v_mul_f32_e32 v179, v80, v155
	v_cvt_pk_bf16_f32 v179, v179, v179
	global_store_short v3, v179, s[72:73] offset:64
	v_mul_f32_e32 v180, v48, v156
	v_cvt_pk_bf16_f32 v180, v180, v180
	global_store_short v3, v180, s[72:73] offset:128
	v_mul_f32_e32 v181, v16, v157
	v_cvt_pk_bf16_f32 v181, v181, v181
	global_store_short v3, v181, s[72:73] offset:192
	s_add_u32 s72, s72, 0x20000
	s_addc_u32 s73, s73, 0
	v_mul_f32_e32 v178, v113, v158
	v_cvt_pk_bf16_f32 v178, v178, v178
	global_store_short v3, v178, s[72:73]
	v_mul_f32_e32 v179, v81, v159
	v_cvt_pk_bf16_f32 v179, v179, v179
	global_store_short v3, v179, s[72:73] offset:64
	v_mul_f32_e32 v180, v49, v160
	v_cvt_pk_bf16_f32 v180, v180, v180
	global_store_short v3, v180, s[72:73] offset:128
	v_mul_f32_e32 v181, v17, v161
	v_cvt_pk_bf16_f32 v181, v181, v181
	global_store_short v3, v181, s[72:73] offset:192
	s_add_u32 s72, s72, 0xa0000
	s_addc_u32 s73, s73, 0
	s_waitcnt vmcnt(16)
	v_mul_f32_e32 v178, v114, v162
	v_cvt_pk_bf16_f32 v178, v178, v178
	global_store_short v3, v178, s[72:73]
	v_mul_f32_e32 v179, v82, v163
	v_cvt_pk_bf16_f32 v179, v179, v179
	global_store_short v3, v179, s[72:73] offset:64
	v_mul_f32_e32 v180, v50, v164
	v_cvt_pk_bf16_f32 v180, v180, v180
	global_store_short v3, v180, s[72:73] offset:128
	v_mul_f32_e32 v181, v18, v165
	v_cvt_pk_bf16_f32 v181, v181, v181
	global_store_short v3, v181, s[72:73] offset:192
	s_add_u32 s72, s72, 0x20000
	s_addc_u32 s73, s73, 0
	v_mul_f32_e32 v178, v115, v166
	v_cvt_pk_bf16_f32 v178, v178, v178
	global_store_short v3, v178, s[72:73]
	v_mul_f32_e32 v179, v83, v167
	v_cvt_pk_bf16_f32 v179, v179, v179
	global_store_short v3, v179, s[72:73] offset:64
	v_mul_f32_e32 v180, v51, v168
	v_cvt_pk_bf16_f32 v180, v180, v180
	global_store_short v3, v180, s[72:73] offset:128
	v_mul_f32_e32 v181, v19, v169
	v_cvt_pk_bf16_f32 v181, v181, v181
	global_store_short v3, v181, s[72:73] offset:192
	s_add_u32 s72, s72, 0x20000
	s_addc_u32 s73, s73, 0
	v_mul_f32_e32 v178, v116, v170
	v_cvt_pk_bf16_f32 v178, v178, v178
	global_store_short v3, v178, s[72:73]
	v_mul_f32_e32 v179, v84, v171
	v_cvt_pk_bf16_f32 v179, v179, v179
	global_store_short v3, v179, s[72:73] offset:64
	v_mul_f32_e32 v180, v52, v172
	v_cvt_pk_bf16_f32 v180, v180, v180
	global_store_short v3, v180, s[72:73] offset:128
	v_mul_f32_e32 v181, v20, v173
	v_cvt_pk_bf16_f32 v181, v181, v181
	global_store_short v3, v181, s[72:73] offset:192
	s_add_u32 s72, s72, 0x20000
	s_addc_u32 s73, s73, 0
	v_mul_f32_e32 v178, v117, v174
	v_cvt_pk_bf16_f32 v178, v178, v178
	global_store_short v3, v178, s[72:73]
	v_mul_f32_e32 v179, v85, v175
	v_cvt_pk_bf16_f32 v179, v179, v179
	global_store_short v3, v179, s[72:73] offset:64
	v_mul_f32_e32 v180, v53, v176
	v_cvt_pk_bf16_f32 v180, v180, v180
	global_store_short v3, v180, s[72:73] offset:128
	v_mul_f32_e32 v181, v21, v177
	v_cvt_pk_bf16_f32 v181, v181, v181
	global_store_short v3, v181, s[72:73] offset:192
